# barhop: non-leader WGs poll cross-XCD TOPGEN directly instead of per-XCC XGEN (one less release hop per grid barrier), on v11
# speedup vs baseline: 1.0010x; 1.0002x over previous
; __device__ __forceinline__ unsigned xb_ld(unsigned* p)              { return __hip_atomic_load(p, __ATOMIC_RELAXED, __HIP_MEMORY_SCOPE_AGENT); }
; __device__ __forceinline__ unsigned xb_add(unsigned* p, unsigned v) { return __hip_atomic_fetch_add(p, v, __ATOMIC_RELAXED, __HIP_MEMORY_SCOPE_AGENT); }
; #define XB_SPIN(cond, bar) do { unsigned _sp = 0; while (cond) { __builtin_amdgcn_s_sleep(1); \
;     if ((++_sp & 255u) == 0u) { if (xb_ld(&(bar)[XB_TMO])) break; if (_sp > XB_SPIN_CAP) { atomicAdd(&(bar)[XB_TMO], 1u); break; } } } } while (0)
; __device__ __forceinline__ void xcd_barrier(const XcdBarrier& b) {
;     ...
;         const unsigned old = xb_add(&bar[XB_XSUB(b.x)], 1u);
;         const unsigned gen = old / nloc;
;         if (old + 1u == (gen + 1u) * nloc) {
;             __builtin_amdgcn_fence(__ATOMIC_RELEASE, "agent");
;             asm volatile("s_waitcnt vmcnt(0)" ::: "memory");
;             const unsigned og = xb_add(&bar[XB_TOP], 1u);
;             const unsigned tg = og / nx;
;             if (og + 1u == (tg + 1u) * nx) xb_add(&bar[XB_TOPGEN], 1u);
;             else XB_SPIN(xb_ld(&bar[XB_TOPGEN]) == tg, bar);
;             __builtin_amdgcn_fence(__ATOMIC_ACQUIRE, "agent");
;             xb_add(&bar[XB_XGEN(b.x)], 1u);
;             asm volatile("s_waitcnt vmcnt(0)" ::: "memory");
;         } else {
;             XB_SPIN(xb_ld(&bar[XB_XGEN(b.x)]) == gen, bar);
.LBB0_837:
	s_or_b64 exec, exec, s[12:13]
	v_cvt_f32_u32_e32 v5, v3
	s_waitcnt vmcnt(0)
	v_readfirstlane_b32 s0, v4
	v_sub_u32_e32 v4, 0, v3
	v_rcp_iflag_f32_e32 v5, v5
	v_add_u32_e32 v6, s0, v0
	v_mul_f32_e32 v5, 0x4f7ffffe, v5
	v_cvt_u32_f32_e32 v5, v5
	v_mul_lo_u32 v0, v4, v5
	v_mul_hi_u32 v0, v5, v0
	v_add_u32_e32 v0, v5, v0
	v_mul_hi_u32 v0, v6, v0
	v_mul_lo_u32 v4, v0, v3
	v_sub_u32_e32 v4, v6, v4
	v_add_u32_e32 v5, 1, v0
	v_cmp_ge_u32_e32 vcc, v4, v3
	s_nop 1
	v_cndmask_b32_e32 v0, v0, v5, vcc
	v_sub_u32_e32 v5, v4, v3
	v_cndmask_b32_e32 v4, v4, v5, vcc
	v_add_u32_e32 v5, 1, v0
	v_cmp_ge_u32_e32 vcc, v4, v3
	v_add_u32_e32 v4, 1, v6
	s_nop 0
	v_cndmask_b32_e32 v0, v0, v5, vcc
	v_mul_lo_u32 v5, v3, v0
	v_add_u32_e32 v3, v5, v3
	v_cmp_ne_u32_e32 vcc, v4, v3
	s_and_saveexec_b64 s[0:1], vcc
	s_xor_b64 s[10:11], exec, s[0:1]
	s_cbranch_execz .LBB0_851
	s_waitcnt lgkmcnt(0)
	v_mov_b32_e32 v2, 0x3500
	global_load_dword v2, v2, s[6:7] sc1
	s_add_u32 s16, s6, 0x3500
	s_addc_u32 s17, s7, 0
	s_waitcnt vmcnt(0)
	v_cmp_eq_u32_e32 vcc, v2, v0
	s_and_saveexec_b64 s[12:13], vcc
	s_cbranch_execz .LBB0_850
	s_mov_b32 s0, 1
	s_mov_b64 s[18:19], 0
	s_branch .LBB0_841

; __device__ __forceinline__ unsigned xb_ld(unsigned* p)              { return __hip_atomic_load(p, __ATOMIC_RELAXED, __HIP_MEMORY_SCOPE_AGENT); }
; __device__ __forceinline__ unsigned xb_add(unsigned* p, unsigned v) { return __hip_atomic_fetch_add(p, v, __ATOMIC_RELAXED, __HIP_MEMORY_SCOPE_AGENT); }
; #define XB_SPIN(cond, bar) do { unsigned _sp = 0; while (cond) { __builtin_amdgcn_s_sleep(1); \
;     if ((++_sp & 255u) == 0u) { if (xb_ld(&(bar)[XB_TMO])) break; if (_sp > XB_SPIN_CAP) { atomicAdd(&(bar)[XB_TMO], 1u); break; } } } } while (0)
; __device__ __forceinline__ void xcd_barrier(const XcdBarrier& b) {
;     ...
;         const unsigned old = xb_add(&bar[XB_XSUB(b.x)], 1u);
;         const unsigned gen = old / nloc;
;         if (old + 1u == (gen + 1u) * nloc) {
;             __builtin_amdgcn_fence(__ATOMIC_RELEASE, "agent");
;             asm volatile("s_waitcnt vmcnt(0)" ::: "memory");
;             const unsigned og = xb_add(&bar[XB_TOP], 1u);
;             const unsigned tg = og / nx;
;             if (og + 1u == (tg + 1u) * nx) xb_add(&bar[XB_TOPGEN], 1u);
;             else XB_SPIN(xb_ld(&bar[XB_TOPGEN]) == tg, bar);
;             __builtin_amdgcn_fence(__ATOMIC_ACQUIRE, "agent");
;             xb_add(&bar[XB_XGEN(b.x)], 1u);
;             asm volatile("s_waitcnt vmcnt(0)" ::: "memory");
;         } else {
;             XB_SPIN(xb_ld(&bar[XB_XGEN(b.x)]) == gen, bar);
.LBB0_908:
	s_or_b64 exec, exec, s[12:13]
	v_cvt_f32_u32_e32 v5, v3
	s_waitcnt vmcnt(0)
	v_readfirstlane_b32 s0, v4
	v_sub_u32_e32 v4, 0, v3
	v_rcp_iflag_f32_e32 v5, v5
	v_add_u32_e32 v6, s0, v0
	v_mul_f32_e32 v5, 0x4f7ffffe, v5
	v_cvt_u32_f32_e32 v5, v5
	v_mul_lo_u32 v0, v4, v5
	v_mul_hi_u32 v0, v5, v0
	v_add_u32_e32 v0, v5, v0
	v_mul_hi_u32 v0, v6, v0
	v_mul_lo_u32 v4, v0, v3
	v_sub_u32_e32 v4, v6, v4
	v_add_u32_e32 v5, 1, v0
	v_cmp_ge_u32_e32 vcc, v4, v3
	s_nop 1
	v_cndmask_b32_e32 v0, v0, v5, vcc
	v_sub_u32_e32 v5, v4, v3
	v_cndmask_b32_e32 v4, v4, v5, vcc
	v_add_u32_e32 v5, 1, v0
	v_cmp_ge_u32_e32 vcc, v4, v3
	v_add_u32_e32 v4, 1, v6
	s_nop 0
	v_cndmask_b32_e32 v0, v0, v5, vcc
	v_mul_lo_u32 v5, v3, v0
	v_add_u32_e32 v3, v5, v3
	v_cmp_ne_u32_e32 vcc, v4, v3
	s_and_saveexec_b64 s[0:1], vcc
	s_xor_b64 s[10:11], exec, s[0:1]
	s_cbranch_execz .LBB0_922
	s_waitcnt lgkmcnt(0)
	v_mov_b32_e32 v2, 0x3500
	global_load_dword v2, v2, s[6:7] sc1
	s_add_u32 s14, s6, 0x3500
	s_addc_u32 s15, s7, 0
	s_waitcnt vmcnt(0)
	v_cmp_eq_u32_e32 vcc, v2, v0
	s_and_saveexec_b64 s[12:13], vcc
	s_cbranch_execz .LBB0_921
	s_mov_b32 s0, 1
	s_mov_b64 s[16:17], 0
	s_branch .LBB0_912
